# previous + 7 redundant VALU ops per tile removed from both P7 softmax bodies (max(x,x) canonicalisations, 0+x row-sum seeds); results unchanged for non-NaN data
# baseline (speedup 1.0000x reference)
.LBB0_737:
	s_nop 8
	v_max_f32_e32 v1, v162, v163
	v_max3_f32 v1, v1, v164, v165
	v_max3_f32 v1, v1, v166, v167
	v_max3_f32 v1, v1, v168, v169
	v_max3_f32 v1, v1, v170, v171
	v_max3_f32 v1, v1, v172, v173
	v_max3_f32 v1, v1, v174, v175
	v_max3_f32 v1, v1, v176, v177
	v_max3_f32 v1, v1, v146, v147
	v_max3_f32 v1, v1, v148, v149
	v_max3_f32 v1, v1, v150, v151
	v_max3_f32 v1, v1, v152, v153
	v_max3_f32 v1, v1, v154, v155
	v_max3_f32 v1, v1, v156, v157
	v_max3_f32 v1, v1, v158, v159
	v_max3_f32 v1, v1, v160, v161
	v_mov_b32_e32 v12, v1
	s_nop 1
	v_permlane32_swap_b32_e32 v1, v12
	v_max_f32_e32 v1, v1, v12
	v_mul_f32_e32 v12, 0x3e0293ee, v1
	v_fma_f32 v1, v1, s97, -v235
	v_cmp_ge_f32_e32 vcc, s80, v1
	v_max_f32_e32 v1, v235, v12
	v_sub_f32_e32 v12, v235, v1
	v_cvt_f32_i32_e32 v13, v234
	s_cmp_eq_u64 vcc, exec
	v_exp_f32_e32 v12, v12
	s_cselect_b64 vcc, -1, 0
	v_cndmask_b32_e32 v235, v1, v235, vcc
	v_fma_f32 v1, v232, v13, v235
	v_cndmask_b32_e64 v16, v12, 1.0, vcc
	v_fma_f32 v12, v232, s81, -v1
	v_sub_f32_e32 v15, v232, v1
	v_fmac_f32_e32 v15, 0x3e0293ee, v163
	v_fma_f32 v163, 2.0, v232, v12
	v_fma_f32 v13, v232, 0, -v1
	v_fmac_f32_e32 v163, 0x3e0293ee, v148
	v_fmac_f32_e32 v13, 0x3e0293ee, v162
	v_fma_f32 v162, v232, 2.0, -v1
	v_exp_f32_e32 v148, v163
	v_fma_f32 v163, v232, s82, -v1
	v_fmac_f32_e32 v162, 0x3e0293ee, v164
	v_fmac_f32_e32 v163, 0x3e0293ee, v165
	v_fmamk_f32 v164, v232, 0x40400000, v12
	v_fmamk_f32 v165, v232, 0x41000000, v12
	v_fmac_f32_e32 v164, 0x3e0293ee, v149
	v_fmac_f32_e32 v165, 0x3e0293ee, v150
	v_fma_f32 v150, v232, s92, -v1
	v_exp_f32_e32 v149, v164
	v_fma_f32 v164, v232, s83, -v1
	v_fmac_f32_e32 v150, 0x3e0293ee, v167
	v_fmac_f32_e32 v164, 0x3e0293ee, v166
	v_exp_f32_e32 v166, v150
	v_fmamk_f32 v150, v232, 0x41100000, v12
	v_fmac_f32_e32 v150, 0x3e0293ee, v151
	v_exp_f32_e32 v167, v150
	v_fma_f32 v150, v232, s93, -v1
	v_fmac_f32_e32 v150, 0x3e0293ee, v168
	v_exp_f32_e32 v168, v150
	v_fmamk_f32 v150, v232, 0x41200000, v12
	v_fmac_f32_e32 v150, 0x3e0293ee, v152
	v_exp_f32_e32 v237, v150
	v_fma_f32 v150, v232, s77, -v1
	v_fmac_f32_e32 v150, 0x3e0293ee, v169
	v_exp_f32_e32 v169, v150
	v_fmamk_f32 v150, v232, 0x41300000, v12
	v_fmac_f32_e32 v150, 0x3e0293ee, v153
	v_exp_f32_e32 v238, v150
	v_fma_f32 v150, v232, s84, -v1
	v_fmac_f32_e32 v150, 0x3e0293ee, v170
	v_exp_f32_e32 v170, v150
	v_fmamk_f32 v150, v232, 0x41800000, v12
	v_fmac_f32_e32 v150, 0x3e0293ee, v154
	v_exp_f32_e32 v239, v150
	v_fma_f32 v150, v232, s33, -v1
	v_fmac_f32_e32 v150, 0x3e0293ee, v171
	v_exp_f32_e32 v154, v150
	v_fmamk_f32 v150, v232, 0x41880000, v12
	v_fmac_f32_e32 v150, 0x3e0293ee, v155
	v_exp_f32_e32 v171, v150
	v_fma_f32 v150, v232, s73, -v1
	v_fmac_f32_e32 v150, 0x3e0293ee, v172
	v_exp_f32_e32 v155, v150
	v_fmamk_f32 v150, v232, 0x41900000, v12
	v_fmac_f32_e32 v150, 0x3e0293ee, v156
	v_fma_f32 v14, 0, v232, v12
	v_exp_f32_e32 v172, v150
	v_fma_f32 v150, v232, s96, -v1
	v_fmac_f32_e32 v14, 0x3e0293ee, v146
	v_add_f32_e32 v17, v232, v12
	v_fmac_f32_e32 v150, 0x3e0293ee, v173
	v_exp_f32_e32 v13, v13
	v_exp_f32_e32 v14, v14
	v_fmac_f32_e32 v17, 0x3e0293ee, v147
	v_exp_f32_e32 v156, v150
	v_fmamk_f32 v150, v232, 0x41980000, v12
	v_exp_f32_e32 v15, v15
	v_exp_f32_e32 v146, v17
	v_fmac_f32_e32 v150, 0x3e0293ee, v157
	v_exp_f32_e32 v162, v162
	v_exp_f32_e32 v173, v150
	v_fma_f32 v150, v232, s86, -v1
	v_exp_f32_e32 v163, v163
	v_fmac_f32_e32 v150, 0x3e0293ee, v174
	v_exp_f32_e32 v164, v164
	v_exp_f32_e32 v165, v165
	v_exp_f32_e32 v157, v150
	v_fmamk_f32 v150, v232, 0x41c00000, v12
	v_add_f32_e32 v17, v15, v13
	v_add_f32_e32 v147, v146, v14
	v_fmac_f32_e32 v150, 0x3e0293ee, v158
	v_add_f32_e32 v17, v162, v17
	v_add_f32_e32 v147, v148, v147
	v_exp_f32_e32 v158, v150
	v_fma_f32 v150, v232, s78, -v1
	v_add_f32_e32 v17, v163, v17
	v_add_f32_e32 v147, v149, v147
	v_fmac_f32_e32 v150, 0x3e0293ee, v175
	v_add_f32_e32 v17, v164, v17
	v_add_f32_e32 v147, v165, v147
	v_exp_f32_e32 v175, v150
	v_fmamk_f32 v150, v232, 0x41c80000, v12
	v_add_f32_e32 v17, v166, v17
	v_add_f32_e32 v147, v167, v147
	v_fmac_f32_e32 v150, 0x3e0293ee, v159
	v_add_f32_e32 v17, v168, v17
	v_add_f32_e32 v147, v237, v147
	v_exp_f32_e32 v159, v150
	v_fma_f32 v150, v232, s79, -v1
	v_add_f32_e32 v17, v169, v17
	v_add_f32_e32 v147, v238, v147
	v_fmac_f32_e32 v150, 0x3e0293ee, v176
	v_add_f32_e32 v17, v170, v17
	v_add_f32_e32 v147, v239, v147
	v_exp_f32_e32 v176, v150
	v_fmamk_f32 v150, v232, 0x41d00000, v12
	v_add_f32_e32 v17, v154, v17
	v_add_f32_e32 v147, v171, v147
	v_fmac_f32_e32 v150, 0x3e0293ee, v160
	v_fma_f32 v1, v232, s87, -v1
	v_fmac_f32_e32 v12, 0x41d80000, v232
	v_add_f32_e32 v17, v155, v17
	v_add_f32_e32 v147, v172, v147
	v_exp_f32_e32 v160, v150
	v_fmac_f32_e32 v1, 0x3e0293ee, v177
	v_fmac_f32_e32 v12, 0x3e0293ee, v161
	v_add_f32_e32 v17, v156, v17
	v_add_f32_e32 v147, v173, v147
	v_exp_f32_e32 v1, v1
	v_exp_f32_e32 v161, v12
	v_add_f32_e32 v17, v157, v17
	v_add_f32_e32 v147, v158, v147
	v_add_f32_e32 v17, v175, v17
	v_add_f32_e32 v147, v159, v147
	v_add_f32_e32 v12, v176, v17
	v_add_f32_e32 v17, v160, v147
	v_add_f32_e32 v12, v1, v12
	v_add_f32_e32 v17, v161, v17
	v_add_f32_e32 v17, v12, v17
	v_mov_b32_e32 v174, v17
	v_cvt_pk_bf16_f32 v150, v13, v15
	v_cvt_pk_bf16_f32 v151, v162, v163
	v_cvt_pk_bf16_f32 v152, v164, v166
	v_cvt_pk_bf16_f32 v153, v168, v169
	v_cvt_pk_bf16_f32 v154, v170, v154
	v_cvt_pk_bf16_f32 v155, v155, v156
	v_cvt_pk_bf16_f32 v156, v157, v175
	v_cvt_pk_bf16_f32 v157, v176, v1
	v_cvt_pk_bf16_f32 v12, v14, v146
	v_cvt_pk_bf16_f32 v13, v148, v149
	v_cvt_pk_bf16_f32 v14, v165, v167
	v_cvt_pk_bf16_f32 v15, v237, v238
	v_cvt_pk_bf16_f32 v146, v239, v171
	v_cvt_pk_bf16_f32 v147, v172, v173
	v_cvt_pk_bf16_f32 v148, v158, v159
	v_cvt_pk_bf16_f32 v149, v160, v161
	v_cmp_neq_f32_e32 vcc, 0, v236
	s_nop 0
	v_permlane32_swap_b32_e32 v17, v174
	v_permlane32_swap_b32_e32 v150, v152
	v_permlane32_swap_b32_e32 v151, v153
	v_permlane32_swap_b32_e32 v154, v156
	v_permlane32_swap_b32_e32 v155, v157
	v_permlane32_swap_b32_e32 v12, v14
	v_permlane32_swap_b32_e32 v13, v15
	v_permlane32_swap_b32_e32 v146, v148
	v_permlane32_swap_b32_e32 v147, v149
	s_cbranch_vccz .LBB0_730
	v_cmp_gt_f32_e32 vcc, 1.0, v16
	s_cbranch_vccz .LBB0_730
	s_and_saveexec_b64 s[6:7], s[4:5]
	s_cbranch_execz .LBB0_729
	ds_write_b32 v223, v16
	s_branch .LBB0_729

.LBB0_758:
	s_nop 8
	v_max_f32_e32 v1, v162, v163
	v_max3_f32 v1, v1, v164, v165
	v_max3_f32 v1, v1, v166, v167
	v_max3_f32 v1, v1, v168, v169
	v_max3_f32 v1, v1, v170, v171
	v_max3_f32 v1, v1, v172, v173
	v_max3_f32 v1, v1, v174, v175
	v_max3_f32 v1, v1, v176, v177
	v_max3_f32 v1, v1, v146, v147
	v_max3_f32 v1, v1, v148, v149
	v_max3_f32 v1, v1, v150, v151
	v_max3_f32 v1, v1, v152, v153
	v_max3_f32 v1, v1, v154, v155
	v_max3_f32 v1, v1, v156, v157
	v_max3_f32 v1, v1, v158, v159
	v_max3_f32 v1, v1, v160, v161
	v_mov_b32_e32 v12, v1
	s_nop 1
	v_permlane32_swap_b32_e32 v1, v12
	v_max_f32_e32 v1, v1, v12
	v_mul_f32_e32 v12, 0x3e0293ee, v1
	v_fma_f32 v1, v1, s97, -v235
	v_cmp_ge_f32_e32 vcc, s80, v1
	v_max_f32_e32 v1, v235, v12
	v_sub_f32_e32 v12, v235, v1
	v_cvt_f32_i32_e32 v13, v234
	s_cmp_eq_u64 vcc, exec
	v_exp_f32_e32 v12, v12
	s_cselect_b64 vcc, -1, 0
	v_cndmask_b32_e32 v235, v1, v235, vcc
	v_fma_f32 v1, v228, v13, v235
	v_cndmask_b32_e64 v16, v12, 1.0, vcc
	v_fma_f32 v12, v228, s81, -v1
	v_sub_f32_e32 v15, v228, v1
	v_fmac_f32_e32 v15, 0x3e0293ee, v163
	v_fma_f32 v163, 2.0, v228, v12
	v_fma_f32 v13, v228, 0, -v1
	v_fmac_f32_e32 v163, 0x3e0293ee, v148
	v_fmac_f32_e32 v13, 0x3e0293ee, v162
	v_fma_f32 v162, v228, 2.0, -v1
	v_exp_f32_e32 v148, v163
	v_fma_f32 v163, v228, s82, -v1
	v_fmac_f32_e32 v162, 0x3e0293ee, v164
	v_fmac_f32_e32 v163, 0x3e0293ee, v165
	v_fmamk_f32 v164, v228, 0x40400000, v12
	v_fmamk_f32 v165, v228, 0x41000000, v12
	v_fmac_f32_e32 v164, 0x3e0293ee, v149
	v_fmac_f32_e32 v165, 0x3e0293ee, v150
	v_fma_f32 v150, v228, s92, -v1
	v_exp_f32_e32 v149, v164
	v_fma_f32 v164, v228, s83, -v1
	v_fmac_f32_e32 v150, 0x3e0293ee, v167
	v_fmac_f32_e32 v164, 0x3e0293ee, v166
	v_exp_f32_e32 v166, v150
	v_fmamk_f32 v150, v228, 0x41100000, v12
	v_fmac_f32_e32 v150, 0x3e0293ee, v151
	v_exp_f32_e32 v167, v150
	v_fma_f32 v150, v228, s93, -v1
	v_fmac_f32_e32 v150, 0x3e0293ee, v168
	v_exp_f32_e32 v168, v150
	v_fmamk_f32 v150, v228, 0x41200000, v12
	v_fmac_f32_e32 v150, 0x3e0293ee, v152
	v_exp_f32_e32 v237, v150
	v_fma_f32 v150, v228, s77, -v1
	v_fmac_f32_e32 v150, 0x3e0293ee, v169
	v_exp_f32_e32 v169, v150
	v_fmamk_f32 v150, v228, 0x41300000, v12
	v_fmac_f32_e32 v150, 0x3e0293ee, v153
	v_exp_f32_e32 v238, v150
	v_fma_f32 v150, v228, s84, -v1
	v_fmac_f32_e32 v150, 0x3e0293ee, v170
	v_exp_f32_e32 v170, v150
	v_fmamk_f32 v150, v228, 0x41800000, v12
	v_fmac_f32_e32 v150, 0x3e0293ee, v154
	v_exp_f32_e32 v239, v150
	v_fma_f32 v150, v228, s33, -v1
	v_fmac_f32_e32 v150, 0x3e0293ee, v171
	v_exp_f32_e32 v154, v150
	v_fmamk_f32 v150, v228, 0x41880000, v12
	v_fmac_f32_e32 v150, 0x3e0293ee, v155
	v_exp_f32_e32 v171, v150
	v_fma_f32 v150, v228, s73, -v1
	v_fmac_f32_e32 v150, 0x3e0293ee, v172
	v_exp_f32_e32 v155, v150
	v_fmamk_f32 v150, v228, 0x41900000, v12
	v_fmac_f32_e32 v150, 0x3e0293ee, v156
	v_fma_f32 v14, 0, v228, v12
	v_exp_f32_e32 v172, v150
	v_fma_f32 v150, v228, s96, -v1
	v_fmac_f32_e32 v14, 0x3e0293ee, v146
	v_add_f32_e32 v17, v228, v12
	v_fmac_f32_e32 v150, 0x3e0293ee, v173
	v_exp_f32_e32 v13, v13
	v_exp_f32_e32 v14, v14
	v_fmac_f32_e32 v17, 0x3e0293ee, v147
	v_exp_f32_e32 v156, v150
	v_fmamk_f32 v150, v228, 0x41980000, v12
	v_exp_f32_e32 v15, v15
	v_exp_f32_e32 v146, v17
	v_fmac_f32_e32 v150, 0x3e0293ee, v157
	v_exp_f32_e32 v162, v162
	v_exp_f32_e32 v173, v150
	v_fma_f32 v150, v228, s86, -v1
	v_exp_f32_e32 v163, v163
	v_fmac_f32_e32 v150, 0x3e0293ee, v174
	v_exp_f32_e32 v164, v164
	v_exp_f32_e32 v165, v165
	v_exp_f32_e32 v157, v150
	v_fmamk_f32 v150, v228, 0x41c00000, v12
	v_add_f32_e32 v17, v15, v13
	v_add_f32_e32 v147, v146, v14
	v_fmac_f32_e32 v150, 0x3e0293ee, v158
	v_add_f32_e32 v17, v162, v17
	v_add_f32_e32 v147, v148, v147
	v_exp_f32_e32 v158, v150
	v_fma_f32 v150, v228, s78, -v1
	v_add_f32_e32 v17, v163, v17
	v_add_f32_e32 v147, v149, v147
	v_fmac_f32_e32 v150, 0x3e0293ee, v175
	v_add_f32_e32 v17, v164, v17
	v_add_f32_e32 v147, v165, v147
	v_exp_f32_e32 v175, v150
	v_fmamk_f32 v150, v228, 0x41c80000, v12
	v_add_f32_e32 v17, v166, v17
	v_add_f32_e32 v147, v167, v147
	v_fmac_f32_e32 v150, 0x3e0293ee, v159
	v_add_f32_e32 v17, v168, v17
	v_add_f32_e32 v147, v237, v147
	v_exp_f32_e32 v159, v150
	v_fma_f32 v150, v228, s79, -v1
	v_add_f32_e32 v17, v169, v17
	v_add_f32_e32 v147, v238, v147
	v_fmac_f32_e32 v150, 0x3e0293ee, v176
	v_add_f32_e32 v17, v170, v17
	v_add_f32_e32 v147, v239, v147
	v_exp_f32_e32 v176, v150
	v_fmamk_f32 v150, v228, 0x41d00000, v12
	v_add_f32_e32 v17, v154, v17
	v_add_f32_e32 v147, v171, v147
	v_fmac_f32_e32 v150, 0x3e0293ee, v160
	v_fma_f32 v1, v228, s87, -v1
	v_fmac_f32_e32 v12, 0x41d80000, v228
	v_add_f32_e32 v17, v155, v17
	v_add_f32_e32 v147, v172, v147
	v_exp_f32_e32 v160, v150
	v_fmac_f32_e32 v1, 0x3e0293ee, v177
	v_fmac_f32_e32 v12, 0x3e0293ee, v161
	v_add_f32_e32 v17, v156, v17
	v_add_f32_e32 v147, v173, v147
	v_exp_f32_e32 v1, v1
	v_exp_f32_e32 v161, v12
	v_add_f32_e32 v17, v157, v17
	v_add_f32_e32 v147, v158, v147
	v_add_f32_e32 v17, v175, v17
	v_add_f32_e32 v147, v159, v147
	v_add_f32_e32 v12, v176, v17
	v_add_f32_e32 v17, v160, v147
	v_add_f32_e32 v12, v1, v12
	v_add_f32_e32 v17, v161, v17
	v_add_f32_e32 v17, v12, v17
	v_mov_b32_e32 v174, v17
	v_cvt_pk_bf16_f32 v150, v13, v15
	v_cvt_pk_bf16_f32 v151, v162, v163
	v_cvt_pk_bf16_f32 v152, v164, v166
	v_cvt_pk_bf16_f32 v153, v168, v169
	v_cvt_pk_bf16_f32 v154, v170, v154
	v_cvt_pk_bf16_f32 v155, v155, v156
	v_cvt_pk_bf16_f32 v156, v157, v175
	v_cvt_pk_bf16_f32 v157, v176, v1
	v_cvt_pk_bf16_f32 v12, v14, v146
	v_cvt_pk_bf16_f32 v13, v148, v149
	v_cvt_pk_bf16_f32 v14, v165, v167
	v_cvt_pk_bf16_f32 v15, v237, v238
	v_cvt_pk_bf16_f32 v146, v239, v171
	v_cvt_pk_bf16_f32 v147, v172, v173
	v_cvt_pk_bf16_f32 v148, v158, v159
	v_cvt_pk_bf16_f32 v149, v160, v161
	v_cmp_neq_f32_e32 vcc, 0, v236
	s_nop 0
	v_permlane32_swap_b32_e32 v17, v174
	v_permlane32_swap_b32_e32 v150, v152
	v_permlane32_swap_b32_e32 v151, v153
	v_permlane32_swap_b32_e32 v154, v156
	v_permlane32_swap_b32_e32 v155, v157
	v_permlane32_swap_b32_e32 v12, v14
	v_permlane32_swap_b32_e32 v13, v15
	v_permlane32_swap_b32_e32 v146, v148
	v_permlane32_swap_b32_e32 v147, v149
	s_cbranch_vccz .LBB0_751
	v_cmp_gt_f32_e32 vcc, 1.0, v16
	s_cbranch_vccz .LBB0_751
	s_and_saveexec_b64 s[6:7], s[4:5]
	s_cbranch_execz .LBB0_750
	ds_write_b32 v232, v16
	s_branch .LBB0_750
